# hand-written weight-prep (f32->bf16 transpose) with 64B-segment loads/stores and 4 tiles in flight, on top of pipelined attention
# speedup vs baseline: 1.0933x; 1.0108x over previous
.Lwp_entry:
	s_waitcnt vmcnt(0)
	v_and_b32_e32 v105, 15, v143
	v_bfe_u32 v106, v143, 4, 2
	v_lshlrev_b32_e32 v107, 5, v106
	v_mov_b32_e32 v108, 0
	v_mov_b32_e32 v109, 0
	v_mov_b32_e32 v110, 0
	v_mov_b32_e32 v111, 0
	v_readfirstlane_b32 s0, v143
	s_lshr_b32 s0, s0, 6
	v_readlane_b32 s1, v253, 0
	s_lshl_b32 s1, s1, 3
	s_add_i32 s21, s1, s0
	v_readlane_b32 s19, v255, 23
	s_lshl_b32 s19, s19, 3
	v_readlane_b32 s4, v253, 15
	v_readlane_b32 s5, v253, 16
	s_add_u32 s6, s50, 0
	s_addc_u32 s7, s51, 0
	s_mov_b32 s8, 10368
	s_mov_b32 s9, 2048
	s_mov_b32 s10, 176
	s_mov_b32 s11, 5632
	s_mov_b32 s12, 0x1745d18
	s_mov_b32 s13, 0
	s_mov_b32 s16, 162
	s_mov_b64 s[14:15], 0
	s_mov_b32 s20, 0
	s_branch .Lwp_mat
.Lwp_ret_0:
	v_readlane_b32 s4, v253, 20
	v_readlane_b32 s5, v253, 21
	s_add_u32 s6, s50, 11534336
	s_addc_u32 s7, s51, 0
	s_mov_b32 s8, 2304
	s_mov_b32 s9, 512
	s_mov_b32 s10, 40
	s_mov_b32 s11, 320
	s_mov_b32 s12, 0x6666667
	s_mov_b32 s13, 0
	s_mov_b32 s16, 36
	v_readlane_b32 s14, v253, 18
	v_readlane_b32 s15, v253, 19
	s_mov_b32 s20, 1
	s_branch .Lwp_mat
.Lwp_ret_1:
	v_readlane_b32 s4, v253, 24
	v_readlane_b32 s5, v253, 25
	s_add_u32 s6, s50, 12189696
	s_addc_u32 s7, s51, 0
	s_mov_b32 s8, 3072
	s_mov_b32 s9, 256
	s_mov_b32 s10, 48
	s_mov_b32 s11, 192
	s_mov_b32 s12, 0x5555556
	s_mov_b32 s13, 0
	s_mov_b32 s16, 48
	v_readlane_b32 s14, v253, 22
	v_readlane_b32 s15, v253, 23
	s_mov_b32 s20, 2
	s_branch .Lwp_mat
.Lwp_ret_2:
	s_mov_b64 s[4:5], s[40:41]
	s_add_u32 s6, s50, 12582912
	s_addc_u32 s7, s51, 0
	s_mov_b32 s8, 1024
	s_mov_b32 s9, 512
	s_mov_b32 s10, 16
	s_mov_b32 s11, 128
	s_mov_b32 s12, 0x10000000
	s_mov_b32 s13, 0
	s_mov_b32 s16, 16
	s_mov_b64 s[14:15], 0
	s_mov_b32 s20, 3
	s_branch .Lwp_mat
.Lwp_ret_3:
	s_mov_b64 s[4:5], s[44:45]
	s_add_u32 s6, s50, 12845056
	s_addc_u32 s7, s51, 0
	s_mov_b32 s8, 4096
	s_mov_b32 s9, 2048
	s_mov_b32 s10, 64
	s_mov_b32 s11, 2048
	s_mov_b32 s12, 0x4000000
	s_mov_b32 s13, 0
	s_mov_b32 s16, 64
	s_mov_b64 s[14:15], 0
	s_mov_b32 s20, 4
	s_branch .Lwp_mat
.Lwp_ret_4:
	v_readlane_b32 s4, v253, 15
	v_readlane_b32 s5, v253, 16
	s_add_u32 s4, s4, 10616832
	s_addc_u32 s5, s5, 0
	s_add_u32 s6, s50, 5767168
	s_addc_u32 s7, s51, 0
	s_mov_b32 s8, 10368
	s_mov_b32 s9, 2048
	s_mov_b32 s10, 176
	s_mov_b32 s11, 5632
	s_mov_b32 s12, 0x1745d18
	s_mov_b32 s13, 0
	s_mov_b32 s16, 162
	s_mov_b64 s[14:15], 0
	s_mov_b32 s20, 5
	s_branch .Lwp_mat
.Lwp_ret_5:
	v_readlane_b32 s4, v253, 20
	v_readlane_b32 s5, v253, 21
	s_add_u32 s4, s4, 589824
	s_addc_u32 s5, s5, 0
	s_add_u32 s6, s50, 11862016
	s_addc_u32 s7, s51, 0
	s_mov_b32 s8, 2304
	s_mov_b32 s9, 512
	s_mov_b32 s10, 40
	s_mov_b32 s11, 320
	s_mov_b32 s12, 0x6666667
	s_mov_b32 s13, 0
	s_mov_b32 s16, 36
	v_readlane_b32 s14, v253, 18
	v_readlane_b32 s15, v253, 19
	s_add_u32 s14, s14, 1024
	s_addc_u32 s15, s15, 0
	s_mov_b32 s20, 6
	s_branch .Lwp_mat
.Lwp_ret_6:
	v_readlane_b32 s4, v253, 24
	v_readlane_b32 s5, v253, 25
	s_add_u32 s4, s4, 393216
	s_addc_u32 s5, s5, 0
	s_add_u32 s6, s50, 12386304
	s_addc_u32 s7, s51, 0
	s_mov_b32 s8, 3072
	s_mov_b32 s9, 256
	s_mov_b32 s10, 48
	s_mov_b32 s11, 192
	s_mov_b32 s12, 0x5555556
	s_mov_b32 s13, 0
	s_mov_b32 s16, 48
	v_readlane_b32 s14, v253, 22
	v_readlane_b32 s15, v253, 23
	s_add_u32 s14, s14, 512
	s_addc_u32 s15, s15, 0
	s_mov_b32 s20, 7
	s_branch .Lwp_mat
.Lwp_ret_7:
	s_mov_b64 s[4:5], s[40:41]
	s_add_u32 s4, s4, 262144
	s_addc_u32 s5, s5, 0
	s_add_u32 s6, s50, 12713984
	s_addc_u32 s7, s51, 0
	s_mov_b32 s8, 1024
	s_mov_b32 s9, 512
	s_mov_b32 s10, 16
	s_mov_b32 s11, 128
	s_mov_b32 s12, 0x10000000
	s_mov_b32 s13, 0
	s_mov_b32 s16, 16
	s_mov_b64 s[14:15], 0
	s_mov_b32 s20, 8
	s_branch .Lwp_mat
.Lwp_ret_8:
	s_mov_b64 s[4:5], s[44:45]
	s_add_u32 s4, s4, 4194304
	s_addc_u32 s5, s5, 0
	s_add_u32 s6, s50, 14942208
	s_addc_u32 s7, s51, 0
	s_mov_b32 s8, 4096
	s_mov_b32 s9, 2048
	s_mov_b32 s10, 64
	s_mov_b32 s11, 2048
	s_mov_b32 s12, 0x4000000
	s_mov_b32 s13, 0
	s_mov_b32 s16, 64
	s_mov_b64 s[14:15], 0
	s_mov_b32 s20, 9
	s_branch .Lwp_mat

.Lwp_mat:
	v_lshlrev_b32_e32 v104, 3, v106
	v_mul_lo_u32 v96, s8, v104
	v_lshl_add_u32 v96, v105, 2, v96
	v_add_u32_e32 v97, s8, v96
	v_add_u32_e32 v98, s8, v97
	v_add_u32_e32 v99, s8, v98
	v_add_u32_e32 v100, s8, v99
	v_add_u32_e32 v101, s8, v100
	v_add_u32_e32 v102, s8, v101
	v_add_u32_e32 v103, s8, v102
	v_mul_lo_u32 v112, s9, v105
	v_lshl_add_u32 v104, v104, 1, v112
	s_mov_b32 s18, s21
.Lwp_loop:
	s_cmp_ge_u32 s18, s11
	s_cbranch_scc1 .Lwp_matdone
	s_mov_b32 s30, 0
	s_cmp_ge_u32 s18, s11
	s_cbranch_scc1 .Lwp_set0_end
	s_mul_hi_u32 s0, s18, s12
	s_lshr_b32 s0, s0, s13
	s_mul_i32 s1, s0, s10
	s_sub_u32 s1, s18, s1
	s_mul_i32 s68, s1, s9
	s_lshl_b32 s68, s68, 4
	s_lshl_b32 s69, s0, 6
	s_add_u32 s68, s68, s69
	s_add_u32 s68, s6, s68
	s_addc_u32 s69, s7, 0
	s_mov_b32 s30, 1
	s_cmp_ge_u32 s1, s16
	s_cbranch_scc1 .Lwp_set0_adv
	s_mov_b32 s30, 2
	s_mul_i32 s64, s0, s8
	s_lshl_b32 s64, s64, 5
	s_lshl_b32 s65, s1, 6
	s_add_u32 s64, s64, s65
	s_add_u32 s64, s4, s64
	s_addc_u32 s65, s5, 0
	s_lshl_b32 s70, s0, 7
	s_add_u32 s70, s14, s70
	s_addc_u32 s71, s15, 0
	global_load_dword v0, v96, s[64:65]
	global_load_dword v1, v97, s[64:65]
	global_load_dword v2, v98, s[64:65]
	global_load_dword v3, v99, s[64:65]
	global_load_dword v4, v100, s[64:65]
	global_load_dword v5, v101, s[64:65]
	global_load_dword v6, v102, s[64:65]
	global_load_dword v7, v103, s[64:65]
	s_cmp_eq_u64 s[14:15], 0
	s_cbranch_scc1 .Lwp_set0_adv
	global_load_dwordx4 v[48:51], v107, s[70:71]
	global_load_dwordx4 v[52:55], v107, s[70:71] offset:16
.Lwp_set0_adv:
	s_add_u32 s18, s18, s19
.Lwp_set0_end:
	s_mov_b32 s31, 0
	s_cmp_ge_u32 s18, s11
	s_cbranch_scc1 .Lwp_set1_end
	s_mul_hi_u32 s0, s18, s12
	s_lshr_b32 s0, s0, s13
	s_mul_i32 s1, s0, s10
	s_sub_u32 s1, s18, s1
	s_mul_i32 s76, s1, s9
	s_lshl_b32 s76, s76, 4
	s_lshl_b32 s77, s0, 6
	s_add_u32 s76, s76, s77
	s_add_u32 s76, s6, s76
	s_addc_u32 s77, s7, 0
	s_mov_b32 s31, 1
	s_cmp_ge_u32 s1, s16
	s_cbranch_scc1 .Lwp_set1_adv
	s_mov_b32 s31, 2
	s_mul_i32 s72, s0, s8
	s_lshl_b32 s72, s72, 5
	s_lshl_b32 s73, s1, 6
	s_add_u32 s72, s72, s73
	s_add_u32 s72, s4, s72
	s_addc_u32 s73, s5, 0
	s_lshl_b32 s78, s0, 7
	s_add_u32 s78, s14, s78
	s_addc_u32 s79, s15, 0
	global_load_dword v8, v96, s[72:73]
	global_load_dword v9, v97, s[72:73]
	global_load_dword v10, v98, s[72:73]
	global_load_dword v11, v99, s[72:73]
	global_load_dword v12, v100, s[72:73]
	global_load_dword v13, v101, s[72:73]
	global_load_dword v14, v102, s[72:73]
	global_load_dword v15, v103, s[72:73]
	s_cmp_eq_u64 s[14:15], 0
	s_cbranch_scc1 .Lwp_set1_adv
	global_load_dwordx4 v[56:59], v107, s[78:79]
	global_load_dwordx4 v[60:63], v107, s[78:79] offset:16

.Lwp_set1_end:
	s_mov_b32 s32, 0
	s_cmp_ge_u32 s18, s11
	s_cbranch_scc1 .Lwp_set2_end
	s_mul_hi_u32 s0, s18, s12
	s_lshr_b32 s0, s0, s13
	s_mul_i32 s1, s0, s10
	s_sub_u32 s1, s18, s1
	s_mul_i32 s82, s1, s9
	s_lshl_b32 s82, s82, 4
	s_lshl_b32 s83, s0, 6
	s_add_u32 s82, s82, s83
	s_add_u32 s82, s6, s82
	s_addc_u32 s83, s7, 0
	s_mov_b32 s32, 1
	s_cmp_ge_u32 s1, s16
	s_cbranch_scc1 .Lwp_set2_adv
	s_mov_b32 s32, 2
	s_mul_i32 s80, s0, s8
	s_lshl_b32 s80, s80, 5
	s_lshl_b32 s81, s1, 6
	s_add_u32 s80, s80, s81
	s_add_u32 s80, s4, s80
	s_addc_u32 s81, s5, 0
	s_lshl_b32 s98, s0, 7
	s_add_u32 s98, s14, s98
	s_addc_u32 s99, s15, 0
	global_load_dword v16, v96, s[80:81]
	global_load_dword v17, v97, s[80:81]
	global_load_dword v18, v98, s[80:81]
	global_load_dword v19, v99, s[80:81]
	global_load_dword v20, v100, s[80:81]
	global_load_dword v21, v101, s[80:81]
	global_load_dword v22, v102, s[80:81]
	global_load_dword v23, v103, s[80:81]
	s_cmp_eq_u64 s[14:15], 0
	s_cbranch_scc1 .Lwp_set2_adv
	global_load_dwordx4 v[64:67], v107, s[98:99]
	global_load_dwordx4 v[68:71], v107, s[98:99] offset:16

.Lwp_set2_end:
	s_mov_b32 s96, 0
	s_cmp_ge_u32 s18, s11
	s_cbranch_scc1 .Lwp_set3_end
	s_mul_hi_u32 s0, s18, s12
	s_lshr_b32 s0, s0, s13
	s_mul_i32 s1, s0, s10
	s_sub_u32 s1, s18, s1
	s_mul_i32 s22, s1, s9
	s_lshl_b32 s22, s22, 4
	s_lshl_b32 s23, s0, 6
	s_add_u32 s22, s22, s23
	s_add_u32 s22, s6, s22
	s_addc_u32 s23, s7, 0
	s_mov_b32 s96, 1
	s_cmp_ge_u32 s1, s16
	s_cbranch_scc1 .Lwp_set3_adv
	s_mov_b32 s96, 2
	s_mul_i32 s100, s0, s8
	s_lshl_b32 s100, s100, 5
	s_lshl_b32 s101, s1, 6
	s_add_u32 s100, s100, s101
	s_add_u32 s100, s4, s100
	s_addc_u32 s101, s5, 0
	s_lshl_b32 s26, s0, 7
	s_add_u32 s26, s14, s26
	s_addc_u32 s27, s15, 0
	global_load_dword v24, v96, s[100:101]
	global_load_dword v25, v97, s[100:101]
	global_load_dword v26, v98, s[100:101]
	global_load_dword v27, v99, s[100:101]
	global_load_dword v28, v100, s[100:101]
	global_load_dword v29, v101, s[100:101]
	global_load_dword v30, v102, s[100:101]
	global_load_dword v31, v103, s[100:101]
	s_cmp_eq_u64 s[14:15], 0
	s_cbranch_scc1 .Lwp_set3_adv
	global_load_dwordx4 v[72:75], v107, s[26:27]
	global_load_dwordx4 v[76:79], v107, s[26:27] offset:16

.Lwp_set3_end:
	s_waitcnt vmcnt(0)
	s_cmp_eq_u32 s30, 0
	s_cbranch_scc1 .Lwp_st0_end
	s_cmp_eq_u32 s30, 1
	s_cbranch_scc1 .Lwp_st0_zero
	s_cmp_eq_u64 s[14:15], 0
	s_cbranch_scc1 .Lwp_st0_pack
	v_mul_f32_e32 v0, v0, v48
	v_mul_f32_e32 v1, v1, v49
	v_mul_f32_e32 v2, v2, v50
	v_mul_f32_e32 v3, v3, v51
	v_mul_f32_e32 v4, v4, v52
	v_mul_f32_e32 v5, v5, v53
	v_mul_f32_e32 v6, v6, v54
	v_mul_f32_e32 v7, v7, v55
.Lwp_st0_pack:
	v_cvt_pk_bf16_f32 v112, v0, v1
	v_cvt_pk_bf16_f32 v113, v2, v3
	v_cvt_pk_bf16_f32 v114, v4, v5
	v_cvt_pk_bf16_f32 v115, v6, v7
	global_store_dwordx4 v104, v[112:115], s[68:69]
	s_nop 1
	s_branch .Lwp_st0_end
.Lwp_st0_zero:
	global_store_dwordx4 v104, v[108:111], s[68:69]
.Lwp_st0_end:
	s_cmp_eq_u32 s31, 0
	s_cbranch_scc1 .Lwp_st1_end
	s_cmp_eq_u32 s31, 1
	s_cbranch_scc1 .Lwp_st1_zero
	s_cmp_eq_u64 s[14:15], 0
	s_cbranch_scc1 .Lwp_st1_pack
	v_mul_f32_e32 v8, v8, v56
	v_mul_f32_e32 v9, v9, v57
	v_mul_f32_e32 v10, v10, v58
	v_mul_f32_e32 v11, v11, v59
	v_mul_f32_e32 v12, v12, v60
	v_mul_f32_e32 v13, v13, v61
	v_mul_f32_e32 v14, v14, v62
	v_mul_f32_e32 v15, v15, v63
.Lwp_st1_pack:
	v_cvt_pk_bf16_f32 v112, v8, v9
	v_cvt_pk_bf16_f32 v113, v10, v11
	v_cvt_pk_bf16_f32 v114, v12, v13
	v_cvt_pk_bf16_f32 v115, v14, v15
	global_store_dwordx4 v104, v[112:115], s[76:77]
	s_nop 1
	s_branch .Lwp_st1_end
.Lwp_st1_zero:
	global_store_dwordx4 v104, v[108:111], s[76:77]
.Lwp_st1_end:
	s_cmp_eq_u32 s32, 0
	s_cbranch_scc1 .Lwp_st2_end
	s_cmp_eq_u32 s32, 1
	s_cbranch_scc1 .Lwp_st2_zero
	s_cmp_eq_u64 s[14:15], 0
	s_cbranch_scc1 .Lwp_st2_pack
	v_mul_f32_e32 v16, v16, v64
	v_mul_f32_e32 v17, v17, v65
	v_mul_f32_e32 v18, v18, v66
	v_mul_f32_e32 v19, v19, v67
	v_mul_f32_e32 v20, v20, v68
	v_mul_f32_e32 v21, v21, v69
	v_mul_f32_e32 v22, v22, v70
	v_mul_f32_e32 v23, v23, v71
.Lwp_st2_pack:
	v_cvt_pk_bf16_f32 v112, v16, v17
	v_cvt_pk_bf16_f32 v113, v18, v19
	v_cvt_pk_bf16_f32 v114, v20, v21
	v_cvt_pk_bf16_f32 v115, v22, v23
	global_store_dwordx4 v104, v[112:115], s[82:83]
	s_nop 1
	s_branch .Lwp_st2_end
.Lwp_st2_zero:
	global_store_dwordx4 v104, v[108:111], s[82:83]
.Lwp_st2_end:
	s_cmp_eq_u32 s96, 0
	s_cbranch_scc1 .Lwp_st3_end
	s_cmp_eq_u32 s96, 1
	s_cbranch_scc1 .Lwp_st3_zero
	s_cmp_eq_u64 s[14:15], 0
	s_cbranch_scc1 .Lwp_st3_pack
	v_mul_f32_e32 v24, v24, v72
	v_mul_f32_e32 v25, v25, v73
	v_mul_f32_e32 v26, v26, v74
	v_mul_f32_e32 v27, v27, v75
	v_mul_f32_e32 v28, v28, v76
	v_mul_f32_e32 v29, v29, v77
	v_mul_f32_e32 v30, v30, v78
	v_mul_f32_e32 v31, v31, v79
.Lwp_st3_pack:
	v_cvt_pk_bf16_f32 v112, v24, v25
	v_cvt_pk_bf16_f32 v113, v26, v27
	v_cvt_pk_bf16_f32 v114, v28, v29
	v_cvt_pk_bf16_f32 v115, v30, v31
	global_store_dwordx4 v104, v[112:115], s[22:23]
	s_nop 1
	s_branch .Lwp_st3_end
.Lwp_st3_zero:
	global_store_dwordx4 v104, v[108:111], s[22:23]

.Lwp_matdone:
	s_cmp_eq_u32 s20, 0
	s_cbranch_scc1 .Lwp_ret_0
	s_cmp_eq_u32 s20, 1
	s_cbranch_scc1 .Lwp_ret_1
	s_cmp_eq_u32 s20, 2
	s_cbranch_scc1 .Lwp_ret_2
	s_cmp_eq_u32 s20, 3
	s_cbranch_scc1 .Lwp_ret_3
	s_cmp_eq_u32 s20, 4
	s_cbranch_scc1 .Lwp_ret_4
	s_cmp_eq_u32 s20, 5
	s_cbranch_scc1 .Lwp_ret_5
	s_cmp_eq_u32 s20, 6
	s_cbranch_scc1 .Lwp_ret_6
	s_cmp_eq_u32 s20, 7
	s_cbranch_scc1 .Lwp_ret_7
	s_cmp_eq_u32 s20, 8
	s_cbranch_scc1 .Lwp_ret_8
	s_cmp_eq_u32 s20, 9
	s_cbranch_scc1 .Lwp_ret_9
.Lwp_done:
.LBB0_180:
	s_waitcnt vmcnt(0)
	s_barrier
	s_mov_b64 s[0:1], exec
	v_readlane_b32 s4, v253, 62
	v_readlane_b32 s5, v253, 63
	s_and_b64 s[4:5], s[0:1], s[4:5]
	s_mov_b64 exec, s[4:5]
	s_cbranch_execz .LBB0_232
	s_getreg_b32 s4, hwreg(HW_REG_XCC_ID, 0, 4)
	s_and_b32 s10, s4, 15
	s_cmp_lg_u32 0, -1
	s_cselect_b32 s4, 0, 0
	s_add_i32 s4, s4, 0x24000
	s_waitcnt vmcnt(9)
	v_mov_b32_e32 v0, s4
	s_waitcnt vmcnt(0) expcnt(0) lgkmcnt(0)
	ds_read_b32 v2, v0
	ds_read_b32 v0, v0 offset:4
	s_waitcnt lgkmcnt(1)
	v_cmp_ne_u32_e32 vcc, 0, v2
	s_cbranch_vccnz .LBB0_196
	s_mov_b32 s11, 1
	s_branch .LBB0_184
